# attention comp-0 softmax without per-tile max: raw scores kept, tile row-sum guards overflow, rare block recomputes with a fresh max
# speedup vs baseline: 1.0873x; 1.0054x over previous
; DI void attn_item(const Params& p, char* smem, u16* qbase, const u16* gabase, const u16* kbase, const u16* vtbase,
;                   int tkv, int nkt, int mylimit, const float* lam_p, const int g_wave) {
;     ...
;   unsigned kso[2], vso[2];
; #pragma unroll
;   for (int i = 0; i < 2; ++i) {
;     const int krow = 4 * (2 * wid + i) + (lane >> 4), kpos = lane & 15;
;     kso[i] = (unsigned)(krow * 1024 + ((kpos ^ (krow & 15)) * 8)) * 2u;
;     const int vrow = 8 * (2 * wid + i) + (lane >> 3), vpos = lane & 7;
;     vso[i] = (unsigned)(vrow * tkv + ((vpos ^ ((vrow >> 1) & 7)) * 8)) * 2u;
;   }
;     ...
;   f32x16 O0[4], O1[4];
; #pragma unroll
;   for (int d = 0; d < 4; ++d) { O0[d] = f32x16{}; O1[d] = f32x16{}; }
;   float l0 = 0.f, l1 = 0.f, m0 = -1e30f, m1 = -1e30f;
;     ...
;   STAGE_KV(0, 0);
;   asm volatile("s_waitcnt vmcnt(0)" ::: "memory");
;   __syncthreads();
.LBB0_708:
	s_lshl_b64 s[42:43], s[42:43], 10
	s_add_i32 s82, s82, 4
	s_and_b64 s[34:35], s[54:55], exec
	s_cselect_b32 s34, s82, 17
	s_add_u32 s54, s66, s51
	v_lshrrev_b32_e32 v6, 3, v2
	s_addc_u32 s55, s67, 0
	s_lshl_b32 s35, s80, 1
	v_lshl_add_u32 v7, s80, 3, v5
	v_lshl_or_b32 v9, s80, 4, v6
	v_xor_b32_e32 v11, v5, v4
	v_xor_b32_e32 v8, v7, v4
	v_mul_lo_u32 v10, v9, s79
	v_lshlrev_b32_e32 v11, 3, v11
	s_or_b32 s35, s35, 1
	v_lshlrev_b32_e32 v8, 4, v8
	v_and_or_b32 v10, v11, 56, v10
	v_lshl_add_u32 v11, s35, 2, v5
	v_lshl_or_b32 v6, s35, 3, v6
	s_lshl_b32 s35, s80, 11
	v_and_b32_e32 v8, 0xf0, v8
	v_xor_b32_e32 v12, v11, v4
	v_mul_lo_u32 v13, v6, s79
	v_lshrrev_b32_e32 v6, 1, v6
	s_add_i32 s35, s35, 16
	v_lshl_or_b32 v7, v7, 11, v8
	v_lshlrev_b32_e32 v12, 4, v12
	v_xor_b32_e32 v14, v6, v4
	s_mov_b32 m0, s35
	v_lshlrev_b32_e32 v10, 1, v10
	v_and_b32_e32 v12, 0xf0, v12
	v_lshlrev_b32_e32 v14, 3, v14
	global_load_lds_dwordx4 v7, s[54:55]
	s_add_i32 m0, s35, 0x8000
	v_lshl_or_b32 v11, v11, 11, v12
	v_and_or_b32 v13, v14, 56, v13
	global_load_lds_dwordx4 v10, s[76:77]
	s_add_i32 m0, s35, 0x400
	v_lshlrev_b32_e32 v13, 1, v13
	global_load_lds_dwordx4 v11, s[54:55]
	s_add_i32 m0, s35, 0x8400
	v_and_b32_e32 v7, 31, v4
	global_load_lds_dwordx4 v13, s[76:77]
	v_lshlrev_b32_e32 v10, 3, v4
	v_and_b32_e32 v182, 0x70, v10
	v_mul_u32_u24_e32 v10, 0x110, v7
	v_lshlrev_b32_e32 v7, 7, v7
	s_add_u32 s54, s76, 0x80
	v_lshrrev_b32_e32 v2, 5, v2
	v_add_u32_e32 v11, 16, v7
	s_addc_u32 s55, s77, 0
	s_lshl_b32 s76, s79, 1
	v_lshlrev_b32_e32 v185, 4, v2
	v_add_u32_e32 v198, v11, v7
	v_lshl_add_u32 v206, v2, 3, v11
	v_mul_lo_u32 v2, s76, v9
	v_bitop3_b32 v7, v5, 7, v4 bitop3:0x48
	v_lshl_add_u32 v2, v7, 4, v2
	v_lshl_add_u64 v[188:189], s[54:55], 0, v[2:3]
	v_or_b32_e32 v2, 8, v9
	s_and_b32 s50, s50, 7
	v_mul_lo_u32 v2, s76, v2
	v_bitop3_b32 v4, v6, 7, v4 bitop3:0x48
	s_lshl_b32 s50, s50, 8
	v_lshl_add_u32 v2, v4, 4, v2
	s_add_u32 s50, s66, s50
	v_lshl_add_u64 v[190:191], s[54:55], 0, v[2:3]
	v_lshlrev_b32_e32 v2, 11, v5
	s_addc_u32 s55, s67, 0
	v_lshl_add_u32 v4, s80, 14, v2
	s_add_u32 s54, s50, 0x20000
	v_or_b32_e32 v2, v4, v8
	s_addc_u32 s55, s55, 0
	v_lshl_add_u64 v[192:193], s[54:55], 0, v[2:3]
	v_or_b32_e32 v2, v4, v12
	s_waitcnt vmcnt(0)
	v_add_u32_e32 v2, 0x2000, v2
	v_mov_b32_e32 v16, v3
	v_mov_b32_e32 v17, v3
	v_add3_u32 v205, s81, v10, v185
	v_lshl_add_u64 v[194:195], s[54:55], 0, v[2:3]
	v_mov_b32_e32 v2, v3
	v_mov_b32_e32 v4, v3
	v_mov_b32_e32 v5, v3
	v_mov_b32_e32 v6, v3
	v_mov_b32_e32 v7, v3
	v_mov_b32_e32 v8, v3
	v_mov_b32_e32 v9, v3
	v_mov_b32_e32 v10, v3
	v_mov_b32_e32 v11, v3
	v_mov_b32_e32 v12, v3
	v_mov_b32_e32 v13, v3
	v_mov_b32_e32 v14, v3
	v_mov_b32_e32 v15, v3
	v_mov_b64_e32 v[128:129], v[16:17]
	v_mov_b64_e32 v[96:97], v[16:17]
	v_mov_b64_e32 v[64:65], v[16:17]
	v_mov_b64_e32 v[32:33], v[16:17]
	v_mov_b64_e32 v[144:145], v[16:17]
	v_mov_b64_e32 v[112:113], v[16:17]
	v_mov_b64_e32 v[80:81], v[16:17]
	v_mov_b64_e32 v[48:49], v[16:17]
	v_xor_b32_e32 v199, v184, v185
	s_mov_b32 s50, 0
	v_mov_b32_e32 v207, 0xf149f2ca
	v_mov_b32_e32 v186, 0
	v_mov_b64_e32 v[126:127], v[14:15]
	v_mov_b64_e32 v[124:125], v[12:13]
	v_mov_b64_e32 v[122:123], v[10:11]
	v_mov_b64_e32 v[120:121], v[8:9]
	v_mov_b64_e32 v[118:119], v[6:7]
	v_mov_b64_e32 v[116:117], v[4:5]
	v_mov_b64_e32 v[114:115], v[2:3]
	v_mov_b64_e32 v[94:95], v[14:15]
	v_mov_b64_e32 v[92:93], v[12:13]
	v_mov_b64_e32 v[90:91], v[10:11]
	v_mov_b64_e32 v[88:89], v[8:9]
	v_mov_b64_e32 v[86:87], v[6:7]
	v_mov_b64_e32 v[84:85], v[4:5]
	v_mov_b64_e32 v[82:83], v[2:3]
	v_mov_b64_e32 v[62:63], v[14:15]
	v_mov_b64_e32 v[60:61], v[12:13]
	v_mov_b64_e32 v[58:59], v[10:11]
	v_mov_b64_e32 v[56:57], v[8:9]
	v_mov_b64_e32 v[54:55], v[6:7]
	v_mov_b64_e32 v[52:53], v[4:5]
	v_mov_b64_e32 v[50:51], v[2:3]
	v_mov_b64_e32 v[30:31], v[14:15]
	v_mov_b64_e32 v[28:29], v[12:13]
	v_mov_b64_e32 v[26:27], v[10:11]
	v_mov_b64_e32 v[24:25], v[8:9]
	v_mov_b64_e32 v[22:23], v[6:7]
	v_mov_b64_e32 v[20:21], v[4:5]
	v_mov_b64_e32 v[18:19], v[2:3]
	v_mov_b64_e32 v[142:143], v[14:15]
	v_mov_b64_e32 v[140:141], v[12:13]
	v_mov_b64_e32 v[138:139], v[10:11]
	v_mov_b64_e32 v[136:137], v[8:9]
	v_mov_b64_e32 v[134:135], v[6:7]
	v_mov_b64_e32 v[132:133], v[4:5]
	v_mov_b64_e32 v[130:131], v[2:3]
	v_mov_b64_e32 v[110:111], v[14:15]
	v_mov_b64_e32 v[108:109], v[12:13]
	v_mov_b64_e32 v[106:107], v[10:11]
	v_mov_b64_e32 v[104:105], v[8:9]
	v_mov_b64_e32 v[102:103], v[6:7]
	v_mov_b64_e32 v[100:101], v[4:5]
	v_mov_b64_e32 v[98:99], v[2:3]
	v_mov_b64_e32 v[78:79], v[14:15]
	v_mov_b64_e32 v[76:77], v[12:13]
	v_mov_b64_e32 v[74:75], v[10:11]
	v_mov_b64_e32 v[72:73], v[8:9]
	v_mov_b64_e32 v[70:71], v[6:7]
	v_mov_b64_e32 v[68:69], v[4:5]
	v_mov_b64_e32 v[66:67], v[2:3]
	v_mov_b64_e32 v[46:47], v[14:15]
	v_mov_b64_e32 v[44:45], v[12:13]
	v_mov_b64_e32 v[42:43], v[10:11]
	v_mov_b64_e32 v[40:41], v[8:9]
	v_mov_b64_e32 v[38:39], v[6:7]
	v_mov_b64_e32 v[36:37], v[4:5]
	v_mov_b64_e32 v[34:35], v[2:3]
	v_mov_b32_e32 v187, 0
	v_mov_b32_e32 v2, 0xf149f2ca
	s_mov_b32 s55, 0
	v_and_b32_e32 v216, 31, v196
	v_and_b32_e32 v217, 4, v216
	v_and_b32_e32 v252, 8, v216
	v_lshlrev_b32_e32 v217, 1, v217
	v_lshrrev_b32_e32 v252, 1, v252
	v_and_b32_e32 v253, 0x13, v216
	v_or3_b32 v253, v253, v217, v252
	v_lshl_add_u32 v198, v253, 8, 16
	v_and_b32_e32 v184, 15, v253
	v_lshlrev_b32_e32 v184, 4, v184
	v_xor_b32_e32 v199, v184, v185
	v_lshl_add_u32 v206, v216, 7, 16
	v_xor_b32_e32 v182, v182, v185
	s_movk_i32 s79, 0x60
	s_movk_i32 s80, 0x80
	s_movk_i32 s81, 0xa0
	s_movk_i32 s82, 0xc0
	s_movk_i32 s83, 0xe0
	s_waitcnt vmcnt(0) lgkmcnt(0)
	s_barrier
	s_add_i32 s54, s55, 1
	s_cmp_ge_u32 s54, s34
	s_cbranch_scc1 .LBB0_711
	s_branch .LBB0_710

; DI void attn_item(const Params& p, char* smem, u16* qbase, const u16* gabase, const u16* kbase, const u16* vtbase,
;                   int tkv, int nkt, int mylimit, const float* lam_p, const int g_wave) {
;     ...
;     if (kt < mylimit) {
;       const char* Kt = Kb + (kt & 1) * KBUF;
;       const char* Vt = Vb + (kt & 1) * VBUF;
;       int zq = 0, kz = (r & 15) * 16, vz = ((r >> 1) & 7) * 16;
;       asm volatile("" : "+v"(zq), "+v"(kz), "+v"(vz));
;       const char* Qk = Qs + zq;
;       bf16x8 pf0[4], pf1[4];
;       SOFTMAX_COMP(0, l0, m0, O0, pf0);
;       __builtin_amdgcn_sched_barrier(0);
;       SOFTMAX_COMP(1, l1, m1, O1, pf1);
.LBB0_711:
	s_cmp_ge_u32 s55, s78
	s_cbranch_scc1 .LBB0_717
	s_and_b32 s55, s50, 0x4000
	v_add_u32_e32 v16, s55, v198
	v_add_u32_e32 v216, v199, v16
	ds_read_b128 v[220:223], v216
	ds_read_b128 v[224:227], v216 offset:8192
	ds_read_b128 v[228:231], v205
	v_xad_u32 v217, v199, 32, v16
	ds_read_b128 v[232:235], v217
	ds_read_b128 v[236:239], v217 offset:8192
	ds_read_b128 v[240:243], v205 offset:32
	v_xad_u32 v216, v199, 64, v16
	ds_read_b128 v[244:247], v216
	ds_read_b128 v[248:251], v216 offset:8192
	ds_read_b128 v[200:203], v205 offset:64
	v_xad_u32 v217, v199, s79, v16
	ds_read_b128 v[208:211], v217
	ds_read_b128 v[212:215], v217 offset:8192
	s_waitcnt lgkmcnt(8)
	v_mfma_f32_32x32x16_bf16 v[162:177], v[220:223], v[228:231], 0
	v_mfma_f32_32x32x16_bf16 v[146:161], v[224:227], v[228:231], 0
	ds_read_b128 v[220:223], v205 offset:96
	s_waitcnt lgkmcnt(6)
	v_mfma_f32_32x32x16_bf16 v[162:177], v[232:235], v[240:243], v[162:177]
	v_mfma_f32_32x32x16_bf16 v[146:161], v[236:239], v[240:243], v[146:161]
	s_waitcnt lgkmcnt(3)
	v_mfma_f32_32x32x16_bf16 v[162:177], v[244:247], v[200:203], v[162:177]
	v_mfma_f32_32x32x16_bf16 v[146:161], v[248:251], v[200:203], v[146:161]
	s_waitcnt lgkmcnt(0)
	v_mfma_f32_32x32x16_bf16 v[162:177], v[208:211], v[220:223], v[162:177]
	v_mfma_f32_32x32x16_bf16 v[146:161], v[212:215], v[220:223], v[146:161]
	v_xad_u32 v254, v199, s80, v16
	ds_read_b128 v[200:203], v254
	ds_read_b128 v[208:211], v254 offset:8192
	ds_read_b128 v[212:215], v205 offset:128
	s_nop 7
	v_fma_f32 v216, v162, s97, -v207
	v_fma_f32 v217, v163, s97, -v207
	v_fma_f32 v252, v164, s97, -v207
	v_fma_f32 v253, v165, s97, -v207
	v_exp_f32_e32 v216, v216
	v_exp_f32_e32 v217, v217
	v_exp_f32_e32 v252, v252
	v_exp_f32_e32 v253, v253
	v_mov_b32_e32 v17, v216
	v_mov_b32_e32 v219, v217
	v_cvt_pk_bf16_f32 v178, v216, v217
	v_cvt_pk_bf16_f32 v179, v252, v253
	v_add_f32_e32 v17, v252, v17
	v_add_f32_e32 v219, v253, v219
	v_fma_f32 v216, v166, s97, -v207
	v_fma_f32 v217, v167, s97, -v207
	v_fma_f32 v252, v168, s97, -v207
	v_fma_f32 v253, v169, s97, -v207
	v_exp_f32_e32 v216, v216
	v_exp_f32_e32 v217, v217
	v_exp_f32_e32 v252, v252
	v_exp_f32_e32 v253, v253
	v_add_f32_e32 v17, v216, v17
	v_add_f32_e32 v219, v217, v219
	v_cvt_pk_bf16_f32 v180, v216, v217
	v_cvt_pk_bf16_f32 v181, v252, v253
	v_add_f32_e32 v17, v252, v17
	v_add_f32_e32 v219, v253, v219
	s_waitcnt lgkmcnt(0)
	v_mfma_f32_32x32x16_bf16 v[220:235], v[200:203], v[212:215], 0
	v_mfma_f32_32x32x16_bf16 v[236:251], v[208:211], v[212:215], 0
	v_xad_u32 v204, v199, s81, v16
	ds_read_b128 v[200:203], v204
	ds_read_b128 v[208:211], v204 offset:8192
	ds_read_b128 v[212:215], v205 offset:160
	v_fma_f32 v216, v170, s97, -v207
	v_fma_f32 v217, v171, s97, -v207
	v_fma_f32 v252, v172, s97, -v207
	v_fma_f32 v253, v173, s97, -v207
	v_exp_f32_e32 v216, v216
	v_exp_f32_e32 v217, v217
	v_exp_f32_e32 v252, v252
	v_exp_f32_e32 v253, v253
	v_add_f32_e32 v17, v216, v17
	v_add_f32_e32 v219, v217, v219
	v_cvt_pk_bf16_f32 v12, v216, v217
	v_cvt_pk_bf16_f32 v13, v252, v253
	v_add_f32_e32 v17, v252, v17
	v_add_f32_e32 v219, v253, v219
	v_fma_f32 v216, v174, s97, -v207
	v_fma_f32 v217, v175, s97, -v207
	v_fma_f32 v252, v176, s97, -v207
	v_fma_f32 v253, v177, s97, -v207
	v_exp_f32_e32 v216, v216
	v_exp_f32_e32 v217, v217
	v_exp_f32_e32 v252, v252
	v_exp_f32_e32 v253, v253
	v_add_f32_e32 v17, v216, v17
	v_add_f32_e32 v219, v217, v219
	v_cvt_pk_bf16_f32 v14, v216, v217
	v_cvt_pk_bf16_f32 v15, v252, v253
	v_add_f32_e32 v17, v252, v17
	v_add_f32_e32 v219, v253, v219
	s_waitcnt lgkmcnt(0)
	v_mfma_f32_32x32x16_bf16 v[220:235], v[200:203], v[212:215], v[220:235]
	v_mfma_f32_32x32x16_bf16 v[236:251], v[208:211], v[212:215], v[236:251]
	v_xad_u32 v254, v199, s82, v16
	ds_read_b128 v[200:203], v254
	ds_read_b128 v[208:211], v254 offset:8192
	ds_read_b128 v[212:215], v205 offset:192
	v_fma_f32 v216, v146, s97, -v207
	v_fma_f32 v217, v147, s97, -v207
	v_fma_f32 v252, v148, s97, -v207
	v_fma_f32 v253, v149, s97, -v207
	v_exp_f32_e32 v216, v216
	v_exp_f32_e32 v217, v217
	v_exp_f32_e32 v252, v252
	v_exp_f32_e32 v253, v253
	v_add_f32_e32 v17, v216, v17
	v_add_f32_e32 v219, v217, v219
	v_cvt_pk_bf16_f32 v8, v216, v217
	v_cvt_pk_bf16_f32 v9, v252, v253
	v_add_f32_e32 v17, v252, v17
	v_add_f32_e32 v219, v253, v219
	v_fma_f32 v216, v150, s97, -v207
	v_fma_f32 v217, v151, s97, -v207
	v_fma_f32 v252, v152, s97, -v207
	v_fma_f32 v253, v153, s97, -v207
	v_exp_f32_e32 v216, v216
	v_exp_f32_e32 v217, v217
	v_exp_f32_e32 v252, v252
	v_exp_f32_e32 v253, v253
	v_add_f32_e32 v17, v216, v17
	v_add_f32_e32 v219, v217, v219
	v_cvt_pk_bf16_f32 v10, v216, v217
	v_cvt_pk_bf16_f32 v11, v252, v253
	v_add_f32_e32 v17, v252, v17
	v_add_f32_e32 v219, v253, v219
	s_waitcnt lgkmcnt(0)
	v_mfma_f32_32x32x16_bf16 v[220:235], v[200:203], v[212:215], v[220:235]
	v_mfma_f32_32x32x16_bf16 v[236:251], v[208:211], v[212:215], v[236:251]
	v_xad_u32 v204, v199, s83, v16
	ds_read_b128 v[200:203], v204
	ds_read_b128 v[208:211], v204 offset:8192
	ds_read_b128 v[212:215], v205 offset:224
	v_fma_f32 v216, v154, s97, -v207
	v_fma_f32 v217, v155, s97, -v207
	v_fma_f32 v252, v156, s97, -v207
	v_fma_f32 v253, v157, s97, -v207
	v_exp_f32_e32 v216, v216
	v_exp_f32_e32 v217, v217
	v_exp_f32_e32 v252, v252
	v_exp_f32_e32 v253, v253
	v_add_f32_e32 v17, v216, v17
	v_add_f32_e32 v219, v217, v219
	v_cvt_pk_bf16_f32 v4, v216, v217
	v_cvt_pk_bf16_f32 v5, v252, v253
	v_add_f32_e32 v17, v252, v17
	v_add_f32_e32 v219, v253, v219
	v_fma_f32 v216, v158, s97, -v207
	v_fma_f32 v217, v159, s97, -v207
	v_fma_f32 v252, v160, s97, -v207
	v_fma_f32 v253, v161, s97, -v207
	v_exp_f32_e32 v216, v216
	v_exp_f32_e32 v217, v217
	v_exp_f32_e32 v252, v252
	v_exp_f32_e32 v253, v253
	v_add_f32_e32 v17, v216, v17
	v_add_f32_e32 v219, v217, v219
	v_cvt_pk_bf16_f32 v6, v216, v217
	v_cvt_pk_bf16_f32 v7, v252, v253
	v_add_f32_e32 v17, v252, v17
	v_add_f32_e32 v219, v253, v219
	s_waitcnt lgkmcnt(0)
	v_mfma_f32_32x32x16_bf16 v[220:235], v[200:203], v[212:215], v[220:235]
	v_mfma_f32_32x32x16_bf16 v[236:251], v[208:211], v[212:215], v[236:251]
	v_add_f32_e32 v17, v17, v219
	v_mov_b32_e32 v219, 0x43800000
	v_cmp_lt_f32_e32 vcc, v219, v17
	s_cmp_lg_u64 vcc, 0
	s_cbranch_scc0 .Lat_ok0
	v_max3_f32 v17, v162, v163, v164
	v_max3_f32 v219, v146, v147, v148
	v_max3_f32 v17, v17, v165, v166
	v_max3_f32 v219, v219, v149, v150
	v_max3_f32 v17, v17, v167, v168
	v_max3_f32 v219, v219, v151, v152
	v_max3_f32 v17, v17, v169, v170
	v_max3_f32 v219, v219, v153, v154
	v_max3_f32 v17, v17, v171, v172
	v_max3_f32 v219, v219, v155, v156
	v_max3_f32 v17, v17, v173, v174
	v_max3_f32 v219, v219, v157, v158
	v_max3_f32 v17, v17, v175, v176
	v_max3_f32 v219, v219, v159, v160
	v_max_f32_e32 v219, v219, v161
	v_max3_f32 v17, v17, v177, v219
	v_mov_b32_e32 v219, v17
	s_nop 1
	v_permlane32_swap_b32_e32 v17, v219
	v_max_f32_e32 v17, v17, v219
	v_mul_f32_e32 v17, s97, v17
	v_max_f32_e32 v219, v207, v17
	v_sub_f32_e32 v216, v207, v219
	v_exp_f32_e32 v216, v216
	v_mov_b32_e32 v207, v219
	s_nop 0
	v_pk_mul_f32 v[144:145], v[144:145], v[216:217] op_sel_hi:[1,0]
	v_pk_mul_f32 v[142:143], v[142:143], v[216:217] op_sel_hi:[1,0]
	v_pk_mul_f32 v[140:141], v[140:141], v[216:217] op_sel_hi:[1,0]
	v_pk_mul_f32 v[138:139], v[138:139], v[216:217] op_sel_hi:[1,0]
	v_pk_mul_f32 v[136:137], v[136:137], v[216:217] op_sel_hi:[1,0]
	v_pk_mul_f32 v[134:135], v[134:135], v[216:217] op_sel_hi:[1,0]
	v_pk_mul_f32 v[132:133], v[132:133], v[216:217] op_sel_hi:[1,0]
	v_pk_mul_f32 v[130:131], v[130:131], v[216:217] op_sel_hi:[1,0]
	v_pk_mul_f32 v[112:113], v[112:113], v[216:217] op_sel_hi:[1,0]
	v_pk_mul_f32 v[110:111], v[110:111], v[216:217] op_sel_hi:[1,0]
	v_pk_mul_f32 v[108:109], v[108:109], v[216:217] op_sel_hi:[1,0]
	v_pk_mul_f32 v[106:107], v[106:107], v[216:217] op_sel_hi:[1,0]
	v_pk_mul_f32 v[104:105], v[104:105], v[216:217] op_sel_hi:[1,0]
	v_pk_mul_f32 v[102:103], v[102:103], v[216:217] op_sel_hi:[1,0]
	v_pk_mul_f32 v[100:101], v[100:101], v[216:217] op_sel_hi:[1,0]
	v_pk_mul_f32 v[98:99], v[98:99], v[216:217] op_sel_hi:[1,0]
	v_pk_mul_f32 v[80:81], v[80:81], v[216:217] op_sel_hi:[1,0]
	v_pk_mul_f32 v[78:79], v[78:79], v[216:217] op_sel_hi:[1,0]
	v_pk_mul_f32 v[76:77], v[76:77], v[216:217] op_sel_hi:[1,0]
	v_pk_mul_f32 v[74:75], v[74:75], v[216:217] op_sel_hi:[1,0]
	v_pk_mul_f32 v[72:73], v[72:73], v[216:217] op_sel_hi:[1,0]
	v_pk_mul_f32 v[70:71], v[70:71], v[216:217] op_sel_hi:[1,0]
	v_pk_mul_f32 v[68:69], v[68:69], v[216:217] op_sel_hi:[1,0]
	v_pk_mul_f32 v[66:67], v[66:67], v[216:217] op_sel_hi:[1,0]
	v_pk_mul_f32 v[48:49], v[48:49], v[216:217] op_sel_hi:[1,0]
	v_pk_mul_f32 v[46:47], v[46:47], v[216:217] op_sel_hi:[1,0]
	v_pk_mul_f32 v[44:45], v[44:45], v[216:217] op_sel_hi:[1,0]
	v_pk_mul_f32 v[42:43], v[42:43], v[216:217] op_sel_hi:[1,0]
	v_pk_mul_f32 v[40:41], v[40:41], v[216:217] op_sel_hi:[1,0]
	v_pk_mul_f32 v[38:39], v[38:39], v[216:217] op_sel_hi:[1,0]
	v_pk_mul_f32 v[36:37], v[36:37], v[216:217] op_sel_hi:[1,0]
	v_pk_mul_f32 v[34:35], v[34:35], v[216:217] op_sel_hi:[1,0]
	v_mul_f32_e32 v186, v186, v216
	v_fma_f32 v216, v162, s97, -v207
	v_fma_f32 v217, v163, s97, -v207
	v_fma_f32 v252, v164, s97, -v207
	v_fma_f32 v253, v165, s97, -v207
	v_exp_f32_e32 v216, v216
	v_exp_f32_e32 v217, v217
	v_exp_f32_e32 v252, v252
	v_exp_f32_e32 v253, v253
	v_mov_b32_e32 v17, v216
	v_mov_b32_e32 v219, v217
	v_cvt_pk_bf16_f32 v178, v216, v217
	v_cvt_pk_bf16_f32 v179, v252, v253
	v_add_f32_e32 v17, v252, v17
	v_add_f32_e32 v219, v253, v219
	v_fma_f32 v216, v166, s97, -v207
	v_fma_f32 v217, v167, s97, -v207
	v_fma_f32 v252, v168, s97, -v207
	v_fma_f32 v253, v169, s97, -v207
	v_exp_f32_e32 v216, v216
	v_exp_f32_e32 v217, v217
	v_exp_f32_e32 v252, v252
	v_exp_f32_e32 v253, v253
	v_add_f32_e32 v17, v216, v17
	v_add_f32_e32 v219, v217, v219
	v_cvt_pk_bf16_f32 v180, v216, v217
	v_cvt_pk_bf16_f32 v181, v252, v253
	v_add_f32_e32 v17, v252, v17
	v_add_f32_e32 v219, v253, v219
	v_fma_f32 v216, v170, s97, -v207
	v_fma_f32 v217, v171, s97, -v207
	v_fma_f32 v252, v172, s97, -v207
	v_fma_f32 v253, v173, s97, -v207
	v_exp_f32_e32 v216, v216
	v_exp_f32_e32 v217, v217
	v_exp_f32_e32 v252, v252
	v_exp_f32_e32 v253, v253
	v_add_f32_e32 v17, v216, v17
	v_add_f32_e32 v219, v217, v219
	v_cvt_pk_bf16_f32 v12, v216, v217
	v_cvt_pk_bf16_f32 v13, v252, v253
	v_add_f32_e32 v17, v252, v17
	v_add_f32_e32 v219, v253, v219
	v_fma_f32 v216, v174, s97, -v207
	v_fma_f32 v217, v175, s97, -v207
	v_fma_f32 v252, v176, s97, -v207
	v_fma_f32 v253, v177, s97, -v207
	v_exp_f32_e32 v216, v216
	v_exp_f32_e32 v217, v217
	v_exp_f32_e32 v252, v252
	v_exp_f32_e32 v253, v253
	v_add_f32_e32 v17, v216, v17
	v_add_f32_e32 v219, v217, v219
	v_cvt_pk_bf16_f32 v14, v216, v217
	v_cvt_pk_bf16_f32 v15, v252, v253
	v_add_f32_e32 v17, v252, v17
	v_add_f32_e32 v219, v253, v219
	v_fma_f32 v216, v146, s97, -v207
	v_fma_f32 v217, v147, s97, -v207
	v_fma_f32 v252, v148, s97, -v207
	v_fma_f32 v253, v149, s97, -v207
	v_exp_f32_e32 v216, v216
	v_exp_f32_e32 v217, v217
	v_exp_f32_e32 v252, v252
	v_exp_f32_e32 v253, v253
	v_add_f32_e32 v17, v216, v17
	v_add_f32_e32 v219, v217, v219
	v_cvt_pk_bf16_f32 v8, v216, v217
	v_cvt_pk_bf16_f32 v9, v252, v253
	v_add_f32_e32 v17, v252, v17
	v_add_f32_e32 v219, v253, v219
	v_fma_f32 v216, v150, s97, -v207
	v_fma_f32 v217, v151, s97, -v207
	v_fma_f32 v252, v152, s97, -v207
	v_fma_f32 v253, v153, s97, -v207
	v_exp_f32_e32 v216, v216
	v_exp_f32_e32 v217, v217
	v_exp_f32_e32 v252, v252
	v_exp_f32_e32 v253, v253
	v_add_f32_e32 v17, v216, v17
	v_add_f32_e32 v219, v217, v219
	v_cvt_pk_bf16_f32 v10, v216, v217
	v_cvt_pk_bf16_f32 v11, v252, v253
	v_add_f32_e32 v17, v252, v17
	v_add_f32_e32 v219, v253, v219
	v_fma_f32 v216, v154, s97, -v207
	v_fma_f32 v217, v155, s97, -v207
	v_fma_f32 v252, v156, s97, -v207
	v_fma_f32 v253, v157, s97, -v207
	v_exp_f32_e32 v216, v216
	v_exp_f32_e32 v217, v217
	v_exp_f32_e32 v252, v252
	v_exp_f32_e32 v253, v253
	v_add_f32_e32 v17, v216, v17
	v_add_f32_e32 v219, v217, v219
	v_cvt_pk_bf16_f32 v4, v216, v217
	v_cvt_pk_bf16_f32 v5, v252, v253
	v_add_f32_e32 v17, v252, v17
	v_add_f32_e32 v219, v253, v219
	v_fma_f32 v216, v158, s97, -v207
	v_fma_f32 v217, v159, s97, -v207
	v_fma_f32 v252, v160, s97, -v207
	v_fma_f32 v253, v161, s97, -v207
	v_exp_f32_e32 v216, v216
	v_exp_f32_e32 v217, v217
	v_exp_f32_e32 v252, v252
	v_exp_f32_e32 v253, v253
	v_add_f32_e32 v17, v216, v17
	v_add_f32_e32 v219, v217, v219
	v_cvt_pk_bf16_f32 v6, v216, v217
	v_cvt_pk_bf16_f32 v7, v252, v253
	v_add_f32_e32 v17, v252, v17
	v_add_f32_e32 v219, v253, v219
	v_add_f32_e32 v17, v17, v219
; DI void attn_item(const Params& p, char* smem, u16* qbase, const u16* gabase, const u16* kbase, const u16* vtbase,
;                   int tkv, int nkt, int mylimit, const float* lam_p, const int g_wave) {
;     ...
; #pragma unroll
;       for (int d = 0; d < 4; ++d) {
;         const int vrow = 32 * d + r;
; #pragma unroll
;         for (int sp = 0; sp < 4; ++sp) {
;           const u32x2 lo = *(const u32x2*)(Vt + vrow * 128 + ((32 * sp) ^ vz) + 8 * hh);
;           const u32x2 hi = *(const u32x2*)(Vt + vrow * 128 + ((32 * sp + 16) ^ vz) + 8 * hh);
;           u32x4 w = {lo[0], lo[1], hi[0], hi[1]};
;           const bf16x8 vf = *reinterpret_cast<bf16x8*>(&w);
;           O0[d] = __builtin_amdgcn_mfma_f32_32x32x16_bf16(vf, pf0[sp], O0[d], 0, 0, 0);
;           O1[d] = __builtin_amdgcn_mfma_f32_32x32x16_bf16(vf, pf1[sp], O1[d], 0, 0, 0);
;         }
.Lat_ok0:
	v_add_f32_e32 v186, v186, v17
	v_add_u32_e32 v16, s55, v206
	v_add_u32_e32 v200, v182, v16
	v_xad_u32 v201, v182, 32, v16
	v_xad_u32 v202, v182, 64, v16
	v_xad_u32 v203, v182, s79, v16
	ds_read_b128 v[162:165], v200 offset:32768
	ds_read_b128 v[166:169], v200 offset:36864
	ds_read_b128 v[170:173], v200 offset:40960
	ds_read_b128 v[174:177], v200 offset:45056
	v_max3_f32 v17, v220, v221, v222
	v_max3_f32 v219, v236, v237, v238
	v_max3_f32 v17, v17, v223, v224
	v_max3_f32 v219, v219, v239, v240
	v_max3_f32 v17, v17, v225, v226
	v_max3_f32 v219, v219, v241, v242
	v_max3_f32 v17, v17, v227, v228
	v_max3_f32 v219, v219, v243, v244
	s_waitcnt lgkmcnt(3)
	v_mfma_f32_32x32x16_bf16 v[130:145], v[162:165], v[178:181], v[130:145]
	v_max3_f32 v17, v17, v229, v230
	v_max3_f32 v219, v219, v245, v246
	v_max3_f32 v17, v17, v231, v232
	v_max3_f32 v219, v219, v247, v248
	v_max3_f32 v17, v17, v233, v234
	v_max3_f32 v219, v219, v249, v250
	v_max_f32_e32 v219, v219, v251
	v_max3_f32 v17, v17, v235, v219
	s_waitcnt lgkmcnt(2)
	v_mfma_f32_32x32x16_bf16 v[98:113], v[166:169], v[178:181], v[98:113]
	v_mov_b32_e32 v219, v17
	s_nop 1
	v_permlane32_swap_b32_e32 v17, v219
	v_max_f32_e32 v17, v17, v219
	v_mul_f32_e32 v17, s97, v17
	v_add_f32_e32 v219, 0x41000000, v2
	v_cmp_le_f32_e32 vcc, v17, v219
	s_cmp_eq_u64 vcc, exec
	s_cbranch_scc1 .Lat_nr1
	v_max_f32_e32 v219, v2, v17
	v_sub_f32_e32 v216, v2, v219
	v_exp_f32_e32 v216, v216
	v_mov_b32_e32 v2, v219
	s_nop 0
	v_pk_mul_f32 v[128:129], v[128:129], v[216:217] op_sel_hi:[1,0]
	v_pk_mul_f32 v[126:127], v[126:127], v[216:217] op_sel_hi:[1,0]
	v_pk_mul_f32 v[124:125], v[124:125], v[216:217] op_sel_hi:[1,0]
	v_pk_mul_f32 v[122:123], v[122:123], v[216:217] op_sel_hi:[1,0]
	v_pk_mul_f32 v[120:121], v[120:121], v[216:217] op_sel_hi:[1,0]
	v_pk_mul_f32 v[118:119], v[118:119], v[216:217] op_sel_hi:[1,0]
	v_pk_mul_f32 v[116:117], v[116:117], v[216:217] op_sel_hi:[1,0]
	v_pk_mul_f32 v[114:115], v[114:115], v[216:217] op_sel_hi:[1,0]
	v_pk_mul_f32 v[96:97], v[96:97], v[216:217] op_sel_hi:[1,0]
	v_pk_mul_f32 v[94:95], v[94:95], v[216:217] op_sel_hi:[1,0]
	v_pk_mul_f32 v[92:93], v[92:93], v[216:217] op_sel_hi:[1,0]
	v_pk_mul_f32 v[90:91], v[90:91], v[216:217] op_sel_hi:[1,0]
	v_pk_mul_f32 v[88:89], v[88:89], v[216:217] op_sel_hi:[1,0]
	v_pk_mul_f32 v[86:87], v[86:87], v[216:217] op_sel_hi:[1,0]
	v_pk_mul_f32 v[84:85], v[84:85], v[216:217] op_sel_hi:[1,0]
	v_pk_mul_f32 v[82:83], v[82:83], v[216:217] op_sel_hi:[1,0]
	v_pk_mul_f32 v[64:65], v[64:65], v[216:217] op_sel_hi:[1,0]
	v_pk_mul_f32 v[62:63], v[62:63], v[216:217] op_sel_hi:[1,0]
	v_pk_mul_f32 v[60:61], v[60:61], v[216:217] op_sel_hi:[1,0]
	v_pk_mul_f32 v[58:59], v[58:59], v[216:217] op_sel_hi:[1,0]
	v_pk_mul_f32 v[56:57], v[56:57], v[216:217] op_sel_hi:[1,0]
	v_pk_mul_f32 v[54:55], v[54:55], v[216:217] op_sel_hi:[1,0]
	v_pk_mul_f32 v[52:53], v[52:53], v[216:217] op_sel_hi:[1,0]
	v_pk_mul_f32 v[50:51], v[50:51], v[216:217] op_sel_hi:[1,0]
	v_pk_mul_f32 v[32:33], v[32:33], v[216:217] op_sel_hi:[1,0]
	v_pk_mul_f32 v[30:31], v[30:31], v[216:217] op_sel_hi:[1,0]
	v_pk_mul_f32 v[28:29], v[28:29], v[216:217] op_sel_hi:[1,0]
	v_pk_mul_f32 v[26:27], v[26:27], v[216:217] op_sel_hi:[1,0]
	v_pk_mul_f32 v[24:25], v[24:25], v[216:217] op_sel_hi:[1,0]
	v_pk_mul_f32 v[22:23], v[22:23], v[216:217] op_sel_hi:[1,0]
	v_pk_mul_f32 v[20:21], v[20:21], v[216:217] op_sel_hi:[1,0]
	v_pk_mul_f32 v[18:19], v[18:19], v[216:217] op_sel_hi:[1,0]
	v_mul_f32_e32 v187, v187, v216
